# PE/PS mapped by the XCC-major block id (same XCD as the G1 tiles they read); G1 visits its second mq/mk tile last
# baseline (speedup 1.0000x reference)
;     DI bool next(int i, Unit& u) const {
;         const long L = (long)i * G + c; if (L >= nwg) return false;
;         int wgid = (int)L; { const int q = nwg / NXCD, r = nwg % NXCD, xcd = wgid % NXCD, off = wgid / NXCD; wgid = (xcd < r ? xcd * (q + 1) : r * (q + 1) + (xcd - r) * q) + off; }
;         const int nig = WGM * nN, gid = wgid / nig, fm = gid * WGM, gsz = (nM - fm) < WGM ? (nM - fm) : WGM;
;         u.pm = fm + ((wgid % nig) % gsz); u.pn = (wgid % nig) / gsz; return true;
; __global__ void __launch_bounds__(NT, 2) fwd_megakernel(Params p) {
;     ...
;     vb = __builtin_amdgcn_readfirstlane(vb); vc = __builtin_amdgcn_readfirstlane(vc);
.LBB0_118:
	s_lshl_b32 s8, s53, 3
	s_lshl_b32 s10, s94, 3
	s_add_u32 s0, s92, 0x100000
	v_writelane_b32 v252, s0, 12
	s_addc_u32 s0, s93, 0
	v_writelane_b32 v252, s0, 13
	s_add_u32 s0, s92, 0x180000
	v_writelane_b32 v252, s0, 14
	s_addc_u32 s0, s93, 0
	v_writelane_b32 v252, s0, 15
	s_add_u32 s0, s92, 0x4000000
	v_writelane_b32 v252, s0, 16
	s_addc_u32 s0, s93, 0
	v_writelane_b32 v252, s0, 17
	s_add_u32 s0, s92, 0x200000
	s_addc_u32 s1, s93, 0
	v_writelane_b32 v252, s0, 18
	v_readfirstlane_b32 s9, v2
	s_waitcnt lgkmcnt(0)
	s_movk_i32 s79, 0x3ff
	v_writelane_b32 v252, s1, 19
	s_mov_b32 s27, 0
	v_readlane_b32 s0, v252, 4
	v_readlane_b32 s1, v252, 5
	s_cmp_gt_i32 s0, -1
	s_cselect_b64 s[0:1], -1, 0
	v_writelane_b32 v252, s0, 20
	v_mbcnt_lo_u32_b32 v2, -1, 0
	s_mov_b32 s95, s9
	v_writelane_b32 v252, s1, 21
	s_add_u32 s0, s92, 0x200
	s_addc_u32 s1, s93, 0
	v_writelane_b32 v252, s0, 22
	v_mov_b32_e32 v204, 0x358637bd
	v_mov_b32_e32 v205, 0x260
	v_writelane_b32 v252, s1, 23
	s_add_u32 s0, s92, 0x1000
	s_addc_u32 s1, s93, 0
	v_writelane_b32 v252, s0, 24
	v_mov_b32_e32 v206, 1
	v_mov_b32_e32 v207, 0x3ecc95a3
	v_writelane_b32 v252, s1, 25
	s_add_u32 s0, s92, 0x1100
	s_addc_u32 s1, s93, 0
	v_writelane_b32 v252, s0, 26
	v_mov_b32_e32 v208, 0x480000
	v_mbcnt_hi_u32_b32 v203, -1, v2
	v_writelane_b32 v252, s1, 27
	s_add_u32 s0, s92, 0x1200
	s_addc_u32 s1, s93, 0
	v_writelane_b32 v252, s0, 28
	v_mov_b32_e32 v209, 0x7f800000
	v_mov_b32_e32 v162, 0x3f317218
	v_writelane_b32 v252, s1, 29
	s_add_u32 s0, s92, 0x1300
	s_addc_u32 s1, s93, 0
	v_writelane_b32 v252, s0, 30
	s_cmp_eq_u32 s26, 15
	v_mov_b64_e32 v[164:165], 0x900
	v_writelane_b32 v252, s1, 31
	s_cselect_b64 s[0:1], -1, 0
	v_writelane_b32 v252, s0, 32
	s_cmp_eq_u32 s26, 14
	v_mov_b64_e32 v[166:167], 0x8ff
	v_writelane_b32 v252, s1, 33
	s_cselect_b64 s[0:1], -1, 0
	v_writelane_b32 v252, s0, 34
	s_cmp_eq_u32 s26, 13
	v_mov_b32_e32 v210, 0x42800000
	v_writelane_b32 v252, s1, 35
	s_cselect_b64 s[0:1], -1, 0
	v_writelane_b32 v252, s0, 36
	s_cmp_eq_u32 s26, 12
	v_mov_b32_e32 v211, 0x42000000
	v_writelane_b32 v252, s1, 37
	s_cselect_b64 s[0:1], -1, 0
	v_writelane_b32 v252, s0, 38
	s_cmp_eq_u32 s26, 11
	v_not_b32_e32 v212, 63
	v_writelane_b32 v252, s1, 39
	s_cselect_b64 s[0:1], -1, 0
	v_writelane_b32 v252, s0, 40
	s_cmp_eq_u32 s26, 10
	v_mov_b32_e32 v213, 0x3d800000
	v_writelane_b32 v252, s1, 41
	s_cselect_b64 s[0:1], -1, 0
	v_writelane_b32 v252, s0, 42
	s_cmp_eq_u32 s26, 9
	v_mov_b32_e32 v214, 0x3f80
	v_writelane_b32 v252, s1, 43
	s_cselect_b64 s[0:1], -1, 0
	v_writelane_b32 v252, s0, 44
	s_cmp_eq_u32 s26, 8
	v_mov_b32_e32 v215, 0xc000
	v_writelane_b32 v252, s1, 45
	s_cselect_b64 s[0:1], -1, 0
	v_writelane_b32 v252, s0, 46
	s_cmp_eq_u32 s26, 7
	v_mov_b32_e32 v216, 0x2000
	v_writelane_b32 v252, s1, 47
	s_cselect_b64 s[0:1], -1, 0
	v_writelane_b32 v252, s0, 48
	s_cmp_eq_u32 s26, 6
	v_mov_b32_e32 v217, 0xc00
	v_writelane_b32 v252, s1, 49
	s_cselect_b64 s[0:1], -1, 0
	v_writelane_b32 v252, s0, 50
	s_cmp_eq_u32 s26, 5
	v_mov_b64_e32 v[168:169], 0x100
	v_writelane_b32 v252, s1, 51
	s_cselect_b64 s[0:1], -1, 0
	v_writelane_b32 v252, s0, 52
	s_cmp_eq_u32 s26, 4
	v_mov_b64_e32 v[170:171], 0xff
	v_writelane_b32 v252, s1, 53
	s_cselect_b64 s[0:1], -1, 0
	v_writelane_b32 v252, s0, 54
	s_cmp_eq_u32 s26, 3
	s_movk_i32 s82, 0x90
	v_writelane_b32 v252, s1, 55
	s_cselect_b64 s[0:1], -1, 0
	v_writelane_b32 v252, s0, 56
	s_cmp_eq_u32 s26, 2
	s_movk_i32 s96, 0x4800
	v_writelane_b32 v252, s1, 57
	s_cselect_b64 s[0:1], -1, 0
	v_writelane_b32 v252, s0, 58
	s_cmp_eq_u32 s26, 1
	s_movk_i32 s85, 0xdff
	v_writelane_b32 v252, s1, 59
	s_cselect_b64 s[0:1], -1, 0
	v_writelane_b32 v252, s0, 60
	s_cmp_eq_u32 s26, 0
	s_movk_i32 s89, 0x2000
	v_writelane_b32 v252, s1, 61
	s_cselect_b64 s[0:1], -1, 0
	v_writelane_b32 v252, s0, 62
	s_mov_b32 s39, 0x3fb8aa3b
	s_mov_b32 s16, 0xc2fc0000
	v_writelane_b32 v252, s1, 63
	s_lshl_b32 s0, s26, 8
	s_add_u32 s0, s92, s0
	s_addc_u32 s1, s93, 0
	s_add_u32 s2, s0, 0x1400
	s_addc_u32 s3, s1, 0
	v_writelane_b32 v251, s2, 0
	v_readlane_b32 s12, v252, 6
	v_readlane_b32 s13, v252, 7
	v_writelane_b32 v251, s3, 1
	s_add_u32 s2, s92, 0x3500
	s_addc_u32 s3, s93, 0
	v_writelane_b32 v251, s2, 2
	s_mov_b32 s26, s27
	s_mov_b32 s58, 0x42fc0000
	v_writelane_b32 v251, s3, 3
	s_add_u32 s2, s92, 0x3400
	s_addc_u32 s3, s93, 0
	s_add_u32 s0, s0, 0x2400
	v_writelane_b32 v251, s2, 4
	s_addc_u32 s1, s1, 0
	s_add_u32 s20, s92, 0x300000
	v_writelane_b32 v251, s3, 5
	v_writelane_b32 v251, s0, 6
	s_addc_u32 s21, s93, 0
	s_movk_i32 s34, 0x210
	v_writelane_b32 v251, s1, 7
	s_add_u32 s0, s92, 0x4c0000
	s_addc_u32 s1, s93, 0
	v_writelane_b32 v251, s0, 8
	s_movk_i32 s59, 0x2400
	s_movk_i32 s37, 0xa0
	v_writelane_b32 v251, s1, 9
	s_add_u32 s0, s92, 0x1000000
	v_writelane_b32 v251, s0, 10
	s_addc_u32 s0, s93, 0
	s_add_u32 s24, s92, 0xc000000
	s_addc_u32 s25, s93, 0
	v_writelane_b32 v251, s0, 11
	s_add_u32 s0, s92, 0x120000
	v_writelane_b32 v251, s0, 12
	s_addc_u32 s0, s93, 0
	v_writelane_b32 v251, s0, 13
	s_ashr_i32 s0, s9, 31
	s_cmpk_lt_i32 s9, 0x900
	s_cselect_b64 s[2:3], -1, 0
	s_mov_b32 s7, s0
	s_lshr_b32 s0, s0, 29
	s_add_i32 s0, s9, s0
	s_ashr_i32 s1, s0, 3
	s_and_b32 s0, s0, -8
	v_writelane_b32 v251, s2, 14
	s_sub_i32 s0, s9, s0
	s_mov_b64 s[56:57], 0x120000
	v_writelane_b32 v251, s3, 15
	s_lshl_b32 s2, s0, 5
	s_cmp_lt_i32 s0, 0
	s_movk_i32 s3, 0x121
	s_cselect_b32 s3, s3, 0x120
	s_mul_i32 s3, s3, s0
	s_mul_i32 s0, s0, 33
	s_cselect_b32 s4, s0, s2
	s_add_i32 s3, s3, s1
	s_mul_hi_i32 s0, s3, 0x38e38e39
	s_lshr_b32 s2, s0, 31
	s_ashr_i32 s0, s0, 5
	s_add_i32 s0, s0, s2
	s_mul_i32 s2, s0, 0x90
	s_sub_i32 s2, s3, s2
	s_bfe_u32 s3, s2, 0x2001d
; DI void phase_prep(const Params& p, int l, int seg, LAS unsigned char* lds, int G, int bid) {
;     ...
;     for (int it = bid * NT + tid; it < (MSEG / 32) * 256; it += G * NT) {
; DI void tables_stage2(const Params& p, int seg, LAS float* mtab, int bid) {
;     ...
;     const bool narrow = (gridDim.x == 256);
;     const int t_lo = narrow ? 4 * (bid >> 6) + wave : wave, t_hi = narrow ? (wave < 4 ? t_lo + 1 : 0) : NB * 4;
;     const bool pub = narrow ? ((bid & 63) == 0) : (bid == 0);
; DI void phase_ps(const Params& p, int seg, LAS unsigned char* lds, int G, int bid) {
;     ...
;     int item = bid;
;     if (item < NITEM) PS_LOAD(item);
;     for (; item < NITEM; item += G) {
;         const int stream = item / NCH, ch = item % NCH;
;         const int grp = stream >> 4, b = (stream >> 2) & 3, hh = stream & 3;
;         const int lrow0 = b * SEG + ch * 64;
	s_add_i32 s3, s2, s3
	s_and_b32 s5, s3, 0xfffc
	s_sub_i32 s2, s2, s5
	s_lshl_b32 s0, s0, 2
	s_sext_i32_i16 s2, s2
	s_add_i32 s6, s0, s2
	s_sext_i32_i16 s0, s3
	s_ashr_i32 s2, s0, 2
	s_lshr_b32 s0, s0, 2
	s_ashr_i32 s35, s94, 31
	v_writelane_b32 v251, s2, 16
	s_add_u32 s2, s92, 0x480000
	s_addc_u32 s3, s93, 0
	v_writelane_b32 v251, s2, 17
	s_mov_b64 s[14:15], 0x80
	s_mov_b64 s[54:55], 0x400
	v_writelane_b32 v251, s3, 18
	s_add_u32 s2, s92, 0x141000
	s_addc_u32 s3, s93, 0
	v_writelane_b32 v251, s2, 19
	s_nop 1
	v_writelane_b32 v251, s3, 20
	v_readfirstlane_b32 s100, v1
	s_mov_b32 s101, s53
	s_mov_b32 s53, s100
	s_ashr_i32 s2, s53, 4
	s_and_b32 s5, s2, -4
	s_and_b64 s[2:3], s[12:13], exec
	s_cselect_b32 s2, s5, 0
	s_and_b32 s5, s53, 63
	v_writelane_b32 v251, s2, 21
	s_and_b64 s[2:3], s[12:13], exec
	s_cselect_b32 s2, s5, s53
	s_cmp_eq_u32 s2, 0
	s_cselect_b64 s[2:3], -1, 0
	v_writelane_b32 v251, s2, 22
	s_nop 1
	v_writelane_b32 v251, s3, 23
	s_add_u32 s2, s92, 0x8000000
	s_addc_u32 s3, s93, 0
	v_writelane_b32 v251, s2, 24
	s_nop 1
	v_writelane_b32 v251, s3, 25
	s_add_u32 s2, s92, 0x121000
	s_addc_u32 s3, s93, 0
	v_writelane_b32 v251, s2, 26
	s_lshl_b32 s78, s94, 9
	s_nop 0
	v_writelane_b32 v251, s3, 27
	s_lshl_b32 s2, s53, 9
	v_writelane_b32 v251, s2, 28
	s_add_u32 s2, s92, 0x580000
	s_addc_u32 s3, s93, 0
	v_writelane_b32 v251, s2, 29
	s_cmpk_lt_i32 s53, 0x800
	s_nop 0
	v_writelane_b32 v251, s3, 30
	s_cselect_b64 s[2:3], -1, 0
	v_writelane_b32 v251, s2, 31
	s_nop 1
	v_writelane_b32 v251, s3, 32
	s_ashr_i32 s2, s53, 31
	s_lshr_b32 s2, s2, 26
	s_add_i32 s2, s53, s2
	s_ashr_i32 s3, s2, 6
	s_and_b32 s2, s2, 0x3ffffc0
	s_sub_i32 s2, s53, s2
	s_cmp_gt_u32 s3, 15
	s_cselect_b64 s[12:13], -1, 0
	s_lshl_b32 s5, s3, 7
	v_writelane_b32 v251, s12, 33
	s_and_b32 s5, s5, 0x600
	s_add_u32 s5, s92, s5
	v_writelane_b32 v251, s13, 34
	v_writelane_b32 v251, s5, 35
	s_addc_u32 s5, s93, 0
	s_lshl_b32 s3, s3, 12
	s_and_b32 s3, s3, 0x3000
	s_lshl_b32 s2, s2, 6
	v_writelane_b32 v251, s5, 36
	s_add_i32 s2, s3, s2
	v_writelane_b32 v251, s2, 37
	s_mov_b32 s53, s101
	s_add_u32 s2, s92, 0x500000
	s_addc_u32 s3, s93, 0
	v_readfirstlane_b32 s5, v1
	v_writelane_b32 v251, s2, 38
	s_cmpk_lt_i32 s5, 0x100
	v_lshrrev_b32_e32 v1, 20, v0
	v_writelane_b32 v251, s3, 39
	s_cselect_b64 s[2:3], -1, 0
	v_writelane_b32 v251, s2, 40
	v_lshrrev_b32_e32 v0, 10, v0
	v_or_b32_e32 v0, v0, v1
	v_writelane_b32 v251, s3, 41
	s_add_u32 s2, s92, 0x1e000000
	s_addc_u32 s3, s93, 0
	v_writelane_b32 v251, s2, 42
	v_and_or_b32 v0, v0, s79, v202
	v_mov_b32_e32 v1, 0
	v_writelane_b32 v251, s3, 43
	s_add_u32 s2, s92, 0x3400000
	v_writelane_b32 v251, s2, 44
	s_addc_u32 s2, s93, 0
	s_cmpk_lt_i32 s9, 0x100
	v_writelane_b32 v251, s2, 45
	s_cselect_b64 s[2:3], -1, 0
	v_writelane_b32 v251, s2, 46
	s_mov_b64 s[12:13], 0
	s_nop 0
	v_writelane_b32 v251, s3, 47
	s_add_u32 s2, s92, 0x10e000
	v_writelane_b32 v251, s2, 48
	s_addc_u32 s2, s93, 0
	v_writelane_b32 v251, s2, 49
	s_add_u32 s2, s92, 0x600000
	v_writelane_b32 v251, s2, 50
	s_addc_u32 s2, s93, 0
	v_writelane_b32 v251, s2, 51
	s_add_u32 s2, s92, 0x4000
	v_writelane_b32 v251, s2, 52
	s_addc_u32 s2, s93, 0
	v_writelane_b32 v251, s2, 53
	s_bfe_i32 s2, s6, 0x10017
	s_lshr_b32 s2, s2, 20
	s_lshl_b32 s3, s6, 8
	s_add_i32 s2, s3, s2
	s_and_b32 s2, s2, 0xfffff000
	s_sub_i32 s2, s3, s2
	s_ashr_i32 s3, s6, 31
	s_lshr_b32 s3, s3, 28
	s_add_i32 s3, s6, s3
	s_lshl_b32 s3, s3, 9
	s_and_b32 s3, s3, 0xffffe000
	v_writelane_b32 v251, s6, 54
	s_add_i32 s2, s2, s3
	s_add_i32 s1, s4, s1
	v_writelane_b32 v251, s2, 55
	s_ashr_i32 s2, s1, 31
	s_lshr_b32 s2, s2, 28
	s_add_i32 s2, s1, s2
	s_and_b32 s3, s2, 0xfff0
	s_sub_i32 s1, s1, s3
	s_bfe_i32 s3, s1, 0x80000
	s_bfe_u32 s3, s3, 0x2000d
	s_add_i32 s3, s1, s3
	s_and_b32 s4, s3, 0xfc
	s_sub_i32 s1, s1, s4
	s_ashr_i32 s2, s2, 4
	s_lshl_b32 s2, s2, 2
	s_sext_i32_i8 s1, s1
	s_add_i32 s4, s2, s1
	s_bfe_i64 s[0:1], s[0:1], 0x100000
	s_lshl_b64 s[0:1], s[0:1], 19
	v_writelane_b32 v251, s0, 56
	s_mov_b32 s6, 1
	s_nop 0
	v_writelane_b32 v251, s1, 57
	s_bfe_i32 s0, s3, 0x80000
	s_sext_i32_i16 s0, s0
	s_lshl_b32 s1, s4, 8
	s_mul_hi_i32 s2, s1, 0x4800
	s_ashr_i32 s1, s0, 2
	s_lshr_b32 s0, s0, 2
	v_writelane_b32 v251, s1, 58
	s_bfe_i64 s[0:1], s[0:1], 0x100000
	s_lshl_b64 s[0:1], s[0:1], 20
	v_writelane_b32 v251, s0, 59
	s_nop 1
	v_writelane_b32 v251, s1, 60
	s_mul_i32 s0, s4, 0x480000
	s_add_u32 s0, s24, s0
	s_addc_u32 s1, s25, s2
	v_writelane_b32 v251, s4, 61
	s_add_u32 s2, s0, 0x240000
	v_writelane_b32 v251, s0, 62
	s_addc_u32 s3, s1, 0
	v_writelane_b32 v250, s2, 0
	v_writelane_b32 v251, s1, 63
	s_mov_b32 s0, s8
	v_writelane_b32 v250, s3, 1
	v_writelane_b32 v250, s0, 2
	s_ashr_i32 s11, s10, 31
	s_lshl_b32 s83, s94, 12
	v_writelane_b32 v250, s1, 3
	s_add_i32 s0, s8, s10
	v_writelane_b32 v250, s0, 4
	s_lshl_b32 s0, s5, 12
	v_writelane_b32 v250, s0, 5
	s_lshl_b32 s0, s5, 6
	v_writelane_b32 v250, s0, 6
	v_writelane_b32 v250, s5, 7
	s_lshl_b32 s0, s5, 3
	v_writelane_b32 v250, s0, 8
	s_add_i32 s0, 0, 0x23ff0
	v_writelane_b32 v250, s0, 9
	s_add_i32 s0, 0, 0x23ff4
	v_writelane_b32 v250, s0, 10
	s_add_i32 s0, 0, 0x16b00
	v_writelane_b32 v250, s0, 11
	s_add_i32 s0, 0, 0x18700
	v_writelane_b32 v250, s0, 12
	v_cmp_eq_u32_e64 s[0:1], 0, v0
	s_add_i32 s36, 0, 0x18c00
	s_mov_b64 s[2:3], -1
	v_writelane_b32 v250, s0, 13
	s_nop 1
	v_writelane_b32 v250, s1, 14
	s_lshl_b64 s[0:1], s[10:11], 5
	v_writelane_b32 v250, s0, 15
	s_nop 1
	v_writelane_b32 v250, s1, 16
	s_lshl_b64 s[0:1], s[10:11], 11
	v_writelane_b32 v250, s0, 17
	s_nop 1
	v_writelane_b32 v250, s1, 18
	s_lshl_b64 s[0:1], s[10:11], 12
	v_writelane_b32 v250, s0, 19
	s_nop 1
	v_writelane_b32 v250, s1, 20
	v_writelane_b32 v250, s97, 21
	v_writelane_b32 v250, s35, 22
	v_writelane_b32 v250, s78, 23
	v_writelane_b32 v250, s83, 24
	s_branch .LBB0_120

;     DI bool next(int i, Unit& u) const {
;         const long L = (long)i * G + c; if (L >= nwg) return false;
;         int wgid = (int)L; { const int q = nwg / NXCD, r = nwg % NXCD, xcd = wgid % NXCD, off = wgid / NXCD; wgid = (xcd < r ? xcd * (q + 1) : r * (q + 1) + (xcd - r) * q) + off; }
;         const int nig = WGM * nN, gid = wgid / nig, fm = gid * WGM, gsz = (nM - fm) < WGM ? (nM - fm) : WGM;
;         u.pm = fm + ((wgid % nig) % gsz); u.pn = (wgid % nig) / gsz; return true;
; template <class Epi>
; DI void gemm_phase(LAS unsigned char* lds, const Gemm g, int G, int c, const Epi& E) {
;     ...
;         const bool has_next = S.next(ui + 1, nxt);
.LBB0_231:
	s_add_i32 s88, s88, 1
	s_mov_b32 s18, 0x87643210
	s_movk_i32 s19, 0x95
	s_cmp_ge_u32 s95, 0x80
	s_cmov_b32 s18, 0x87653210
	s_cmov_b32 s19, 0x94
	s_lshl_b32 s17, s88, 2
	s_lshr_b64 s[18:19], s[18:19], s17
	s_and_b32 s17, s18, 15
	s_mul_i32 s6, s17, s35
	s_mul_hi_u32 s9, s17, s94
	s_add_i32 s9, s9, s6
	s_mul_i32 s6, s17, s94
	s_add_u32 s40, s6, s95
	s_addc_u32 s41, s9, s7
	v_cmp_gt_i64_e32 vcc, s[40:41], v[166:167]
	v_cmp_lt_i64_e64 s[42:43], s[40:41], v[164:165]
	s_cbranch_vccnz .LBB0_233
	s_ashr_i32 s6, s40, 31
	s_lshr_b32 s6, s6, 29
	s_add_i32 s6, s40, s6
	s_ashr_i32 s9, s6, 3
	s_and_b32 s6, s6, -8
	s_sub_i32 s6, s40, s6
	s_cmp_lt_i32 s6, 0
	s_movk_i32 s11, 0x121
	s_cselect_b32 s11, s11, 0x120
	s_mul_i32 s6, s11, s6
	s_add_i32 s6, s6, s9
	s_mul_hi_i32 s9, s6, 0x38e38e39
	s_lshr_b32 s11, s9, 31
	s_ashr_i32 s9, s9, 5
	s_add_i32 s9, s9, s11
	s_lshl_b32 s11, s9, 2
	s_sub_i32 s17, 64, s11
	s_min_i32 s17, s17, 4
	s_abs_i32 s18, s17
	v_cvt_f32_u32_e32 v2, s18
	s_sub_i32 s22, 0, s18
	s_mulk_i32 s9, 0x90
	s_sub_i32 s6, s6, s9
	v_rcp_iflag_f32_e32 v2, v2
	s_abs_i32 s9, s6
	s_xor_b32 s19, s6, s17
	s_ashr_i32 s19, s19, 31
	v_mul_f32_e32 v2, 0x4f7ffffe, v2
	v_cvt_u32_f32_e32 v2, v2
	s_nop 0
	v_readfirstlane_b32 s23, v2
	s_mul_i32 s22, s22, s23
	s_mul_hi_u32 s22, s23, s22
	s_add_i32 s23, s23, s22
	s_mul_hi_u32 s22, s9, s23
	s_mul_i32 s23, s22, s18
	s_sub_i32 s9, s9, s23
	s_add_i32 s28, s22, 1
	s_sub_i32 s23, s9, s18
	s_cmp_ge_u32 s9, s18
	s_cselect_b32 s22, s28, s22
	s_cselect_b32 s9, s23, s9
	s_add_i32 s23, s22, 1
	s_cmp_ge_u32 s9, s18
	s_cselect_b32 s9, s23, s22
	s_xor_b32 s9, s9, s19
	s_sub_i32 s46, s9, s19
	s_mul_i32 s9, s46, s17
	s_sub_i32 s6, s6, s9
	s_add_i32 s89, s6, s11

; #define LAS __attribute__((address_space(3)))
; #define MX_BAR() do { asm volatile("s_waitcnt lgkmcnt(0)" ::: "memory"); __builtin_amdgcn_s_barrier(); asm volatile("" ::: "memory"); } while (0)
; DI void phase_ps(const Params& p, int seg, LAS unsigned char* lds, int G, int bid) {
;     ...
;     int item = bid;
;     if (item < NITEM) PS_LOAD(item);
;     for (; item < NITEM; item += G) {
;         const int stream = item / NCH, ch = item % NCH;
;         const int grp = stream >> 4, b = (stream >> 2) & 3, hh = stream & 3;
;         const int lrow0 = b * SEG + ch * 64;
;         bf16_t* cellb = P + grp * 1024 + hh * 256;
;         { int ts_ = tid; asm volatile("" : "+v"(ts_));
; #pragma unroll
;           for (int i = 0; i < 4; ++i) { const int idx = ts_ + 512 * i, row = idx >> 5, c16 = idx & 31;
;               *(LAS u32x4*)(lds + PS_QI + row * QP + c16 * 16) = pq[i]; *(LAS u32x4*)(lds + PS_KI + row * QP + c16 * 16) = pk[i]; *(LAS u32x4*)(lds + PS_VI + row * QP + c16 * 16) = pv[i]; } }
;         if (item + G < NITEM) PS_LOAD(item + G);
;         MX_BAR();
;         { int ln = lane; asm volatile("" : "+v"(ln)); const int i16 = ln & 15, g4 = ln >> 4; const int lq = 16 * li + i16;
;           f32x4 sa0 = {0.f, 0.f, 0.f, 0.f}, sa1 = {0.f, 0.f, 0.f, 0.f};
;           if (2 * ks <= li) {
.LBB0_494:
	s_ashr_i32 s17, s6, 6
	s_and_b32 s11, s17, 3
	s_ashr_i32 s18, s6, 8
	s_waitcnt vmcnt(0)
	v_mov_b32_e32 v36, v90
	v_readlane_b32 s1, v251, 35
	s_add_u32 s8, s1, s44
	v_readlane_b32 s19, v251, 36
	v_lshlrev_b32_e32 v0, 4, v36
	v_add_u32_e32 v2, 0x600, v36
	s_addc_u32 s9, s19, s45
	v_and_b32_e32 v0, 0x1f0, v0
	v_ashrrev_i32_e32 v2, 5, v2
	v_readlane_b32 s22, v251, 37
	v_lshl_add_u64 v[10:11], s[8:9], 0, v[0:1]
	v_and_b32_e32 v91, 63, v90
	v_add_u32_e32 v4, s22, v2
	v_mad_i64_i32 v[2:3], s[8:9], v4, s96, v[10:11]
	s_add_u32 s8, s1, s42
	s_addc_u32 s9, s19, s43
	v_lshl_add_u64 v[12:13], s[8:9], 0, v[0:1]
	v_mad_i64_i32 v[4:5], s[8:9], s0, v4, 0
	s_add_u32 s8, s1, s40
	s_addc_u32 s9, s19, s41
	v_lshl_add_u64 v[16:17], s[8:9], 0, v[0:1]
	v_add_u32_e32 v0, 0x400, v36
	v_lshlrev_b64 v[14:15], 1, v[4:5]
	v_ashrrev_i32_e32 v0, 5, v0
	v_lshl_add_u64 v[6:7], v[12:13], 0, v[14:15]
	v_lshl_add_u64 v[14:15], v[16:17], 0, v[14:15]
	v_add_u32_e32 v0, s22, v0
	global_load_dwordx4 v[2:5], v[2:3], off
	s_nop 0
	global_load_dwordx4 v[6:9], v[6:7], off
	v_mad_i64_i32 v[18:19], s[8:9], v0, s96, v[10:11]
	global_load_dwordx4 v[46:49], v[14:15], off
	global_load_dwordx4 v[42:45], v[18:19], off
	v_mad_i64_i32 v[14:15], s[8:9], s0, v0, 0
	v_add_u32_e32 v0, 0x200, v36
	v_lshlrev_b64 v[14:15], 1, v[14:15]
	v_ashrrev_i32_e32 v0, 5, v0
	v_lshl_add_u64 v[18:19], v[12:13], 0, v[14:15]
	v_add_u32_e32 v0, s22, v0
	v_lshl_add_u64 v[14:15], v[16:17], 0, v[14:15]
	global_load_dwordx4 v[26:29], v[18:19], off
	global_load_dwordx4 v[30:33], v[14:15], off
	v_mad_i64_i32 v[18:19], s[8:9], s0, v0, 0
	v_mad_i64_i32 v[14:15], s[8:9], v0, s96, v[10:11]
	v_lshlrev_b64 v[34:35], 1, v[18:19]
	v_ashrrev_i32_e32 v0, 5, v36
	v_lshl_add_u64 v[22:23], v[12:13], 0, v[34:35]
	v_add_u32_e32 v0, s22, v0
	global_load_dwordx4 v[18:21], v[14:15], off
	s_nop 0
	global_load_dwordx4 v[22:25], v[22:23], off
	v_lshl_add_u64 v[14:15], v[16:17], 0, v[34:35]
	v_mad_i64_i32 v[10:11], s[8:9], v0, s96, v[10:11]
	global_load_dwordx4 v[38:41], v[14:15], off
	global_load_dwordx4 v[34:37], v[10:11], off
	v_mad_i64_i32 v[10:11], s[0:1], s0, v0, 0
	v_lshlrev_b64 v[10:11], 1, v[10:11]
	v_lshl_add_u64 v[12:13], v[12:13], 0, v[10:11]
	v_lshl_add_u64 v[14:15], v[16:17], 0, v[10:11]
	global_load_dwordx4 v[10:13], v[12:13], off
	s_nop 0
	global_load_dwordx4 v[14:17], v[14:15], off
	s_lshl_b32 s8, s11, 4
	s_lshl_b32 s0, s18, 1
	s_cmp_le_i32 s0, s11
	s_cselect_b64 s[0:1], -1, 0
	s_lshl_b32 s9, s18, 5
	s_and_b32 s18, s6, 0xffffffc0
	s_add_i32 s30, s18, 0
	s_or_b32 s11, s9, 16
	s_add_i32 s30, s30, 0x10800
	s_lshl_b32 s40, s17, 5
	s_cmp_lt_u32 s6, 64
	s_cselect_b64 s[42:43], -1, 0
	s_ashr_i32 s41, s40, 31
	s_lshl_b32 s31, s94, 6
	v_readlane_b32 s38, v250, 6
	v_readlane_b32 s22, v250, 7
	s_branch .LBB0_496
